# barrier-path trimming on v051: one workgroup barrier instead of two at the fused seams, group-barrier polls without back-off
# speedup vs baseline: 1.0056x; 1.0015x over previous
.LBB0_2063:
	s_or_b64 exec, exec, s[0:1]
	s_cmpk_gt_i32 s90, 0x3ff
	v_readlane_b32 s68, v251, 50
	v_readlane_b32 s69, v251, 51
	s_waitcnt lgkmcnt(0)
	s_cbranch_scc1 .LBB0_2167
	v_readlane_b32 s0, v251, 7
	v_and_b32_e32 v112, 15, v152
	v_lshrrev_b32_e32 v113, 4, v152
	s_nop 1
	s_and_b32 s34, s0, 3
	s_lshr_b32 s35, s0, 2
	v_lshrrev_b32_e32 v220, 3, v153
	v_and_b32_e32 v221, 7, v153
	v_and_b32_e32 v222, 7, v220
	v_xor_b32_e32 v222, v222, v221
	v_lshlrev_b32_e32 v222, 4, v222
	v_lshl_add_u32 v114, v220, 7, v222
	v_mul_u32_u24_e32 v123, 0x90, v220
	v_lshl_add_u32 v123, v221, 4, v123
	v_add_u32_e32 v123, 0x2400, v123
	v_mul_u32_u24_e32 v117, 0x600, v220
	v_lshl_add_u32 v117, v221, 4, v117
	v_lshlrev_b32_e32 v118, 12, v220
	v_lshl_add_u32 v118, v221, 4, v118
	v_mul_u32_u24_e32 v116, 0x90, v112
	v_lshl_add_u32 v116, v113, 3, v116
	v_and_b32_e32 v222, 7, v112
	v_xor_b32_e32 v222, v222, v113
	v_lshlrev_b32_e32 v222, 4, v222
	v_lshl_add_u32 v115, v112, 7, v222
	v_xor_b32_e32 v122, 64, v115
	s_lshl_b32 s1, s0, 13
	s_add_i32 s1, s1, 0x9000
	v_lshl_add_u32 v250, v152, 4, s1
	v_mov_b32_e32 v226, 0xf149f2ca
	v_mov_b32_e32 v227, 0xff61b1e6
	v_mov_b32_e32 v203, 0x41000000
	v_mov_b32_e32 v238, 0
	v_mov_b32_e32 v224, 0xff800000
	s_mov_b32 s26, s90
	s_mov_b32 s50, 0

.Lgb_poll0:
	global_load_dword v2, v0, s[96:97] sc1
	s_waitcnt vmcnt(0)
	v_readfirstlane_b32 vcc_lo, v2
	s_sub_i32 vcc_lo, vcc_lo, s3
	s_cmp_ge_i32 vcc_lo, 0
	s_cbranch_scc1 .Lgb_done0
	s_add_i32 vcc_hi, vcc_hi, 1
	s_cmp_lt_u32 vcc_hi, 0x40000
	s_cbranch_scc0 .Lgb_done0
	s_nop 0
	s_branch .Lgb_poll0

.LBB0_2486:
	s_or_b64 exec, exec, s[0:1]
	s_waitcnt lgkmcnt(0)
.LBB0_2487:
	s_cmp_lt_i32 s86, 13
	s_cselect_b64 s[0:1], -1, 0
	s_and_b64 s[2:3], s[0:1], s[2:3]
	s_andn2_b64 vcc, exec, s[2:3]
	s_cbranch_vccnz .LBB0_2496
	s_cmpk_gt_i32 s90, 0x3ff
	s_cbranch_scc1 .LBB0_2496
	v_and_b32_e32 v1, 15, v153
	v_readlane_b32 s2, v251, 7
	v_mov_b32_e32 v139, 0
	v_lshlrev_b32_e32 v9, 4, v153
	v_lshl_or_b32 v137, s2, 4, v1
	v_and_b32_e32 v140, 0x70, v9
	v_mov_b32_e32 v141, v139
	v_mul_u32_u24_e32 v204, 0x90, v1
	v_mul_u32_u24_e32 v213, 0x210, v1
	v_or_b32_e32 v1, 48, v152
	v_lshl_add_u64 v[2:3], s[96:97], 0, v[140:141]
	s_mov_b64 s[4:5], 0x1d200000
	v_mul_u32_u24_e32 v214, 0x210, v1
	v_mul_u32_u24_e32 v215, 0x90, v1
	v_or_b32_e32 v1, 0x70, v152
	v_lshlrev_b32_e32 v7, 5, v153
	v_lshl_add_u64 v[142:143], v[2:3], 0, s[4:5]
	s_mov_b32 s4, 0xfc00
	s_mov_b32 s5, 0xff00
	v_mov_b32_e32 v12, 0x8000
	v_mul_u32_u24_e32 v216, 0x90, v1
	v_or_b32_e32 v1, 0xb0, v152
	v_lshrrev_b32_e32 v5, 4, v152
	v_and_b32_e32 v2, 0x7c00, v7
	v_and_b32_e32 v4, 0x7f00, v7
	v_add_u32_e32 v3, 0x4000, v7
	v_or_b32_e32 v11, 0x8000, v7
	v_bitop3_b32 v10, v7, s4, v12 bitop3:0xc8
	v_bitop3_b32 v12, v7, s5, v12 bitop3:0xc8
	v_add_u32_e32 v7, 0xc000, v7
	v_mul_u32_u24_e32 v217, 0x90, v1
	v_or_b32_e32 v1, 0xf0, v152
	v_lshlrev_b32_e32 v136, 3, v5
	v_mul_u32_u24_e32 v218, 0x90, v1
	v_lshlrev_b32_e32 v18, 2, v5
	v_lshlrev_b32_e32 v1, 1, v7
	v_and_b32_e32 v5, 7, v153
	v_and_b32_e32 v1, 0x3fe00, v1
	v_lshlrev_b32_e32 v5, 4, v5
	s_mov_b32 s6, 0x1d200080
	v_or3_b32 v144, v1, v5, s6
	v_lshlrev_b32_e32 v1, 1, v11
	v_add_u32_e32 v15, 0x200, v153
	v_and_b32_e32 v1, 0x1fe00, v1
	v_lshrrev_b32_e32 v17, 5, v15
	v_lshrrev_b32_e32 v15, 3, v15
	v_or3_b32 v146, v1, v5, s6
	v_lshlrev_b32_e32 v1, 1, v3
	v_lshrrev_b32_e32 v13, 3, v153
	v_mul_u32_u24_e32 v208, 0x90, v15
	v_or_b32_e32 v15, 0x400, v153
	v_and_b32_e32 v1, 0x1fe00, v1
	s_add_u32 s2, s96, 0xb000000
	v_and_b32_e32 v6, 0xfc00, v3
	v_and_b32_e32 v8, 0xff00, v3
	v_lshrrev_b32_e32 v19, 5, v15
	v_or3_b32 v148, v1, v5, s6
	v_lshlrev_b32_e32 v1, 9, v13
	v_and_b32_e32 v3, 31, v153
	s_addc_u32 s3, s97, 0
	v_lshrrev_b32_e32 v15, 3, v15
	v_or3_b32 v150, v1, v5, s6
	v_lshlrev_b32_e32 v1, 11, v19
	v_lshlrev_b32_e32 v3, 4, v3
	s_mov_b32 s6, 0x1ca20000
	s_add_u32 s9, s96, 0x1ca00000
	v_and_b32_e32 v141, 0x1f0, v9
	v_lshrrev_b32_e32 v9, 5, v153
	v_mul_u32_u24_e32 v210, 0x90, v15
	v_add_u32_e32 v15, 0x600, v153
	v_or3_b32 v154, v1, v3, s6
	v_lshlrev_b32_e32 v1, 11, v17
	s_addc_u32 s16, s97, 0
	v_lshlrev_b32_e32 v0, 3, v153
	v_lshrrev_b32_e32 v20, 5, v15
	v_or3_b32 v156, v1, v3, s6
	v_lshlrev_b32_e32 v1, 11, v9
	v_and_b32_e32 v0, 0xf8, v0
	v_and_b32_e32 v14, 0x1fc00, v7
	v_and_b32_e32 v16, 0x1ff00, v7
	v_lshrrev_b32_e32 v15, 3, v15
	s_add_u32 s4, s96, 0x3000000
	v_or3_b32 v158, v1, v3, s6
	v_lshl_or_b32 v138, v20, 11, v3
	s_mov_b64 s[6:7], 0x1ca20000
	v_and_b32_e32 v203, 48, v153
	v_mul_u32_u24_e32 v205, 0x210, v9
	v_mul_u32_u24_e32 v206, 0x90, v13
	v_mul_u32_u24_e32 v207, 0x210, v17
	v_mul_u32_u24_e32 v209, 0x210, v19
	v_mul_u32_u24_e32 v211, 0x210, v20
	v_mul_u32_u24_e32 v212, 0x90, v15
	s_addc_u32 s5, s97, 0
	v_mov_b32_e32 v145, v139
	v_mov_b32_e32 v147, v139
	v_mov_b32_e32 v149, v139
	v_mov_b32_e32 v151, v139
	v_mov_b32_e32 v155, v139
	v_mov_b32_e32 v157, v139
	v_mov_b32_e32 v159, v139
	v_lshl_add_u64 v[160:161], v[138:139], 0, s[6:7]
	s_mov_b32 s7, 0
	v_lshlrev_b32_e32 v162, 1, v136
	v_lshlrev_b32_e32 v164, 1, v0
	v_lshlrev_b32_e32 v166, 1, v2
	v_lshlrev_b32_e32 v168, 1, v4
	v_lshlrev_b32_e32 v170, 1, v6
	v_lshlrev_b32_e32 v172, 1, v8
	v_lshlrev_b32_e32 v174, 1, v10
	v_lshlrev_b32_e32 v176, 1, v12
	v_lshlrev_b32_e32 v178, 1, v14
	v_lshlrev_b32_e32 v180, 1, v16
	s_mov_b32 s8, 0x3d800000
	s_mov_b32 s17, 0xf149f2ca
	s_mov_b64 s[10:11], 0x80
	s_mov_b64 s[12:13], 0x20000
	v_lshlrev_b32_e32 v182, 1, v18
	s_mov_b32 s18, s90
	s_branch .LBB0_2491

.Lgb_poll1:
	global_load_dword v2, v0, s[96:97] sc1
	s_waitcnt vmcnt(0)
	v_readfirstlane_b32 vcc_lo, v2
	s_sub_i32 vcc_lo, vcc_lo, s5
	s_cmp_ge_i32 vcc_lo, 0
	s_cbranch_scc1 .Lgb_done1
	s_add_i32 vcc_hi, vcc_hi, 1
	s_cmp_lt_u32 vcc_hi, 0x40000
	s_cbranch_scc0 .Lgb_done1
	s_nop 0
	s_branch .Lgb_poll1

.Lgb_lag2:
	v_readfirstlane_b32 vcc_lo, v3
	s_cmp_ge_u32 vcc_lo, 0x100
	s_cbranch_scc1 .Lgb_lagok2
	s_add_i32 vcc_hi, vcc_hi, 1
	s_cmp_lt_u32 vcc_hi, 0x40000
	s_cbranch_scc0 .Lgb_lagok2
	s_nop 0
	global_load_dword v3, v1, s[96:97] sc1
	s_waitcnt vmcnt(0)
	s_branch .Lgb_lag2
